# P1 REG3 k-tile column sums: DPP row reductions instead of 64 serialized ds_bpermute round trips
# speedup vs baseline: 1.0961x; 1.0001x over previous
; template <int REG>
; DI void epi_inproj(const Params& p, f32x4 (&acc)[2][2][4][2], int pm, int pn, LAS unsigned char* shm) {
;     ...
;     const f32x4 q0 = *(const f32x4*)((const float*)(ws + OFF_RSTD1Q) + T0 + (wr * 16 + fr) * 8), q1 = *(const f32x4*)((const float*)(ws + OFF_RSTD1Q) + T0 + (wr * 16 + fr) * 8 + 4);
; #pragma unroll
;     for (int m = 0; m < 4; ++m) { rsr[0][m] = q0[m]; rsr[1][m] = q1[m]; }
;     ...
;     const bool isk = pn >= 14;
;     const float* nw = isk ? p.k_norm_w : p.q_norm_w;
;     bf16_t* dstb = (bf16_t*)(ws + (isk ? OFF_MK : OFF_MQ));
;     const int hh = (pn & 1) * 4 + wc;
;     f32x4 w4[2][2], cs4[2][2];
; #pragma unroll
;     for (int bj = 0; bj < 2; ++bj)
; #pragma unroll
;       for (int n = 0; n < 2; ++n) { w4[bj][n] = *(const f32x4*)(nw + 32 * bj + 8 * fq + 4 * n); cs4[bj][n] = (f32x4){0.f, 0.f, 0.f, 0.f}; }
; #pragma unroll
;     for (int ai = 0; ai < 2; ++ai)
; #pragma unroll
;       for (int m = 0; m < 4; ++m) { asm volatile("" ::: "memory");
;         const int r = 128 * ai + 64 * wr + 16 * m + fr, t = t0 + r;
;         const float rs = rsr[ai][m];
;         f32x4 v[2][2]; float ss = 0.f;
; #pragma unroll
;         for (int bj = 0; bj < 2; ++bj)
; #pragma unroll
;           for (int n = 0; n < 2; ++n) { v[bj][n] = acc[ai][bj][m][n] * rs; ss += v[bj][n][0] * v[bj][n][0] + v[bj][n][1] * v[bj][n][1] + v[bj][n][2] * v[bj][n][2] + v[bj][n][3] * v[bj][n][3]; }
;         ss += __shfl_xor(ss, 16); ss += __shfl_xor(ss, 32);
;         const float rn = __builtin_amdgcn_rsqf(ss * (1.0f / 64.0f) + 1e-6f) * (isk ? 1.0f : 0.125f * 1.4426950408889634f);
;         bf16_t* dst = dstb + ((long)((b * 8 + hh) * SEQ + t)) * 64 + 8 * fq;
.LBB0_435:
	v_mov_b32_e32 v168, v194
	s_lshl_b32 s48, s22, 8
	s_ashr_i32 s49, s48, 31
	v_and_b32_e32 v170, 15, v168
	s_and_b32 s46, s22, 31
	v_ashrrev_i32_e32 v175, 8, v168
	s_lshl_b64 s[48:49], s[48:49], 2
	v_lshlrev_b32_e32 v112, 3, v170
	s_add_u32 s48, s65, s48
	v_lshl_or_b32 v112, v175, 7, v112
	s_addc_u32 s49, s67, s49
	v_ashrrev_i32_e32 v113, 31, v112
	v_lshl_add_u64 v[112:113], v[112:113], 2, s[48:49]
	global_load_dwordx4 v[148:151], v[112:113], off
	s_nop 0
	global_load_dwordx4 v[112:115], v[112:113], off offset:16
	s_lshl_b32 s23, s40, 2
	s_cmp_gt_i32 s40, 13
	s_cselect_b64 s[48:49], -1, 0
	v_bfe_u32 v118, v168, 4, 2
	v_cndmask_b32_e64 v174, v167, 1.0, s[48:49]
	s_and_b64 s[48:49], s[48:49], exec
	v_lshlrev_b32_e32 v171, 5, v118
	s_cselect_b32 s48, s44, s42
	s_cselect_b32 s49, s45, s43
	global_load_dwordx4 v[124:127], v171, s[48:49] offset:16
	global_load_dwordx4 v[132:135], v171, s[48:49]
	v_and_b32_e32 v117, 64, v165
	v_xor_b32_e32 v116, 16, v165
	v_add_u32_e32 v172, 64, v117
	v_cmp_lt_i32_e32 vcc, v116, v172
	v_xor_b32_e32 v173, 32, v165
	v_lshlrev_b32_e32 v195, 6, v175
	v_cndmask_b32_e32 v176, v165, v116, vcc
	global_load_dwordx4 v[116:119], v171, s[48:49] offset:144
	global_load_dwordx4 v[128:131], v171, s[48:49] offset:128
	v_lshlrev_b32_e32 v176, 2, v176
	v_cmp_lt_i32_e32 vcc, v173, v172
	s_cselect_b32 s47, s76, 0x10300000
	s_add_u32 s48, s26, s47
	v_cndmask_b32_e32 v177, v165, v173, vcc
	v_lshlrev_b32_e32 v175, 2, v177
	s_addc_u32 s49, s27, 0
	s_ashr_i32 s22, s22, 2
	v_ashrrev_i32_e32 v169, 6, v168
	s_and_b32 s23, s23, 4
	s_and_b32 s22, s22, -8
	v_and_b32_e32 v173, 3, v169
	s_or_b32 s47, s22, s23
	v_lshl_or_b32 v196, s46, 8, v170
	v_and_b32_e32 v156, 48, v168
	s_cmp_gt_i32 s40, 13
	s_cselect_b32 s100, 0x3c0, 0
	s_mov_b32 s101, 0
	s_cselect_b64 s[98:99], -1, 0
	v_bfe_u32 v238, v170, 2, 1
	v_mul_u32_u24_e32 v238, 0x600, v238
	v_mad_u32_u24 v238, v156, 15, v238
	v_lshrrev_b32_e32 v240, 3, v170
	v_mul_u32_u24_e32 v240, 0x3c0, v240
	v_sub_u32_e32 v238, v238, v240
	v_and_b32_e32 v240, 3, v170
	v_mul_u32_u24_e32 v240, 0x70, v240
	v_sub_u32_e32 v238, v238, v240
	v_add_u32_e32 v240, 0xfffff880, v238
	v_cndmask_b32_e64 v238, 0, v238, s[98:99]
	v_cndmask_b32_e64 v240, 0, v240, s[98:99]
	v_ashrrev_i32_e32 v239, 31, v238
	v_ashrrev_i32_e32 v241, 31, v240
	s_cmp_lt_i32 s40, 14
	s_waitcnt vmcnt(0)
	v_pk_mul_f32 v[178:179], v[144:145], v[148:149] op_sel_hi:[1,0]
	v_pk_mul_f32 v[140:141], v[140:141], v[148:149] op_sel_hi:[1,0]
	v_pk_mul_f32 v[136:137], v[136:137], v[148:149] op_sel_hi:[1,0]
	v_pk_mul_f32 v[182:183], v[122:123], v[148:149] op_sel_hi:[1,0]
	v_pk_mul_f32 v[184:185], v[120:121], v[148:149] op_sel_hi:[1,0]
	v_mov_b32_e32 v122, v179
	v_mov_b32_e32 v123, v141
	v_pk_mul_f32 v[146:147], v[146:147], v[148:149] op_sel_hi:[1,0]
	v_pk_mul_f32 v[180:181], v[142:143], v[148:149] op_sel_hi:[1,0]
	v_mov_b32_e32 v120, v178
	v_mov_b32_e32 v121, v140
	v_mov_b32_e32 v188, v185
	v_mov_b32_e32 v189, v137
	v_pk_mul_f32 v[122:123], v[122:123], v[122:123]
	v_pk_mul_f32 v[138:139], v[138:139], v[148:149] op_sel_hi:[1,0]
	v_mov_b32_e32 v142, v146
	v_mov_b32_e32 v143, v180
	v_mov_b32_e32 v186, v184
	v_mov_b32_e32 v187, v136
	v_pk_mul_f32 v[188:189], v[188:189], v[188:189]
	v_pk_fma_f32 v[120:121], v[120:121], v[120:121], v[122:123]
	v_mov_b32_e32 v144, v147
	v_mov_b32_e32 v145, v181
	v_mov_b32_e32 v190, v182
	v_mov_b32_e32 v191, v138
	v_pk_fma_f32 v[122:123], v[186:187], v[186:187], v[188:189]
	v_pk_fma_f32 v[120:121], v[142:143], v[142:143], v[120:121]
	v_mov_b32_e32 v192, v183
	v_mov_b32_e32 v193, v139
	v_pk_fma_f32 v[122:123], v[190:191], v[190:191], v[122:123]
	v_pk_fma_f32 v[120:121], v[144:145], v[144:145], v[120:121]
	v_pk_fma_f32 v[122:123], v[192:193], v[192:193], v[122:123]
	v_add_f32_e32 v120, v120, v121
	v_add_f32_e32 v120, v123, v120
	v_add_f32_e32 v120, v122, v120
	ds_bpermute_b32 v121, v176, v120
	v_or_b32_e32 v122, s47, v173
	v_lshlrev_b32_e32 v122, 13, v122
	v_add3_u32 v144, v196, v195, v122
	v_ashrrev_i32_e32 v145, 31, v144
	s_waitcnt lgkmcnt(0)
	v_add_f32_e32 v120, v120, v121
	ds_bpermute_b32 v121, v175, v120
	v_lshl_add_u64 v[142:143], s[48:49], 0, v[156:157]
	v_pk_mul_f32 v[108:109], v[108:109], v[148:149] op_sel:[0,1]
	v_pk_mul_f32 v[100:101], v[100:101], v[148:149] op_sel:[0,1]
	v_pk_mul_f32 v[192:193], v[96:97], v[148:149] op_sel:[0,1]
	s_waitcnt lgkmcnt(0)
; DI u32x2 pk4(f32x4 v) { u32x2 r; r.x = pk2(v[0], v[1]); r.y = pk2(v[2], v[3]); return r; }
; template <int REG>
; DI void epi_inproj(const Params& p, f32x4 (&acc)[2][2][4][2], int pm, int pn, LAS unsigned char* shm) {
;     ...
;       for (int m = 0; m < 4; ++m) { asm volatile("" ::: "memory");
;         const int r = 128 * ai + 64 * wr + 16 * m + fr, t = t0 + r;
;         const float rs = rsr[ai][m];
;         f32x4 v[2][2]; float ss = 0.f;
; #pragma unroll
;         for (int bj = 0; bj < 2; ++bj)
; #pragma unroll
;           for (int n = 0; n < 2; ++n) { v[bj][n] = acc[ai][bj][m][n] * rs; ss += v[bj][n][0] * v[bj][n][0] + v[bj][n][1] * v[bj][n][1] + v[bj][n][2] * v[bj][n][2] + v[bj][n][3] * v[bj][n][3]; }
;         ss += __shfl_xor(ss, 16); ss += __shfl_xor(ss, 32);
;         const float rn = __builtin_amdgcn_rsqf(ss * (1.0f / 64.0f) + 1e-6f) * (isk ? 1.0f : 0.125f * 1.4426950408889634f);
;         bf16_t* dst = dstb + ((long)((b * 8 + hh) * SEQ + t)) * 64 + 8 * fq;
; #pragma unroll
;         for (int bj = 0; bj < 2; ++bj) {
;           const f32x4 o0 = v[bj][0] * rn * w4[bj][0], o1 = v[bj][1] * rn * w4[bj][1]; cs4[bj][0] += o0; cs4[bj][1] += o1;
;           const u32x2 h0 = pk4(o0), h1 = pk4(o1);
;           *(u32x4*)(dst + 32 * bj) = (u32x4){h0.x, h0.y, h1.x, h1.y};
;         }
;       }
	v_add_f32_e32 v120, v120, v121
	v_fmamk_f32 v120, v120, 0x3c800000, v166
	v_rsq_f32_e32 v122, v120
	v_lshlrev_b64 v[120:121], 7, v[144:145]
	v_lshl_add_u64 v[186:187], v[142:143], 0, v[120:121]
	v_lshl_add_u64 v[186:187], v[186:187], 0, v[238:239]
	v_pk_mul_f32 v[110:111], v[110:111], v[148:149] op_sel:[0,1]
	v_mul_f32_e32 v156, v174, v122
	v_pk_mul_f32 v[120:121], v[178:179], v[156:157] op_sel_hi:[1,0]
	v_pk_mul_f32 v[122:123], v[146:147], v[156:157] op_sel_hi:[1,0]
	v_pk_mul_f32 v[146:147], v[140:141], v[156:157] op_sel_hi:[1,0]
	v_pk_mul_f32 v[178:179], v[180:181], v[156:157] op_sel_hi:[1,0]
	v_pk_mul_f32 v[188:189], v[136:137], v[156:157] op_sel_hi:[1,0]
	v_pk_mul_f32 v[190:191], v[138:139], v[156:157] op_sel_hi:[1,0]
	v_pk_mul_f32 v[138:139], v[134:135], v[122:123]
	v_pk_mul_f32 v[140:141], v[132:133], v[120:121]
	v_pk_mul_f32 v[122:123], v[126:127], v[178:179]
	v_pk_mul_f32 v[136:137], v[124:125], v[146:147]
	v_cvt_pk_bf16_f32 v178, v140, v141
	v_cvt_pk_bf16_f32 v179, v138, v139
	v_cvt_pk_bf16_f32 v180, v136, v137
	v_cvt_pk_bf16_f32 v181, v122, v123
	global_store_dwordx4 v[186:187], v[178:181], off
	v_pk_mul_f32 v[146:147], v[106:107], v[148:149] op_sel:[0,1]
	v_mov_b32_e32 v106, v109
	v_pk_mul_f32 v[178:179], v[104:105], v[148:149] op_sel:[0,1]
	v_pk_mul_f32 v[120:121], v[130:131], v[190:191]
	v_mov_b32_e32 v107, v179
	v_mov_b32_e32 v104, v108
	v_mov_b32_e32 v105, v178
	v_pk_mul_f32 v[106:107], v[106:107], v[106:107]
	v_pk_mul_f32 v[190:191], v[98:99], v[148:149] op_sel:[0,1]
	v_mov_b32_e32 v98, v193
	v_mov_b32_e32 v99, v101
	v_pk_fma_f32 v[104:105], v[104:105], v[104:105], v[106:107]
	v_mov_b32_e32 v106, v110
	v_mov_b32_e32 v107, v146
	v_pk_mul_f32 v[180:181], v[102:103], v[148:149] op_sel:[0,1]
	v_mov_b32_e32 v96, v192
	v_mov_b32_e32 v97, v100
	v_pk_mul_f32 v[98:99], v[98:99], v[98:99]
	v_pk_fma_f32 v[104:105], v[106:107], v[106:107], v[104:105]
	v_mov_b32_e32 v106, v111
	v_mov_b32_e32 v107, v147
	v_pk_fma_f32 v[96:97], v[96:97], v[96:97], v[98:99]
	v_mov_b32_e32 v98, v190
	v_mov_b32_e32 v99, v180
	v_pk_fma_f32 v[104:105], v[106:107], v[106:107], v[104:105]
	v_pk_fma_f32 v[96:97], v[98:99], v[98:99], v[96:97]
	v_mov_b32_e32 v98, v191
	v_mov_b32_e32 v99, v181
	v_pk_fma_f32 v[96:97], v[98:99], v[98:99], v[96:97]
	v_add_f32_e32 v98, v104, v105
	v_add_f32_e32 v97, v97, v98
	v_add_f32_e32 v104, v96, v97
	ds_bpermute_b32 v105, v176, v104
	v_pk_mul_f32 v[98:99], v[184:185], v[156:157] op_sel_hi:[1,0]
	v_pk_mul_f32 v[96:97], v[182:183], v[156:157] op_sel_hi:[1,0]
	v_pk_mul_f32 v[102:103], v[128:129], v[188:189]
	v_pk_mul_f32 v[96:97], v[118:119], v[96:97]
	s_waitcnt lgkmcnt(0)
	v_add_f32_e32 v107, v104, v105
	ds_bpermute_b32 v145, v175, v107
	v_pk_mul_f32 v[98:99], v[116:117], v[98:99]
	v_cvt_pk_bf16_f32 v104, v102, v103
	v_cvt_pk_bf16_f32 v105, v120, v121
	v_cvt_pk_bf16_f32 v106, v98, v99
	s_waitcnt lgkmcnt(0)
	v_add_f32_e32 v107, v107, v145
	v_fmamk_f32 v107, v107, 0x3c800000, v166
	v_rsq_f32_e32 v145, v107
	v_cvt_pk_bf16_f32 v107, v96, v97
	v_lshl_add_u64 v[186:187], v[186:187], 0, s[100:101]
	global_store_dwordx4 v[186:187], v[104:107], off offset:64
	v_pk_mul_f32 v[92:93], v[92:93], v[150:151] op_sel_hi:[1,0]
	v_mul_f32_e32 v156, v174, v145
	v_or_b32_e32 v104, 16, v144
	v_ashrrev_i32_e32 v105, 31, v104
	v_lshlrev_b64 v[104:105], 7, v[104:105]
	v_lshl_add_u64 v[182:183], v[142:143], 0, v[104:105]
	v_lshl_add_u64 v[182:183], v[182:183], 0, v[240:241]
	v_pk_mul_f32 v[104:105], v[108:109], v[156:157] op_sel_hi:[1,0]
	v_pk_mul_f32 v[106:107], v[110:111], v[156:157] op_sel_hi:[1,0]
	v_pk_mul_f32 v[110:111], v[132:133], v[104:105]
	v_pk_mul_f32 v[108:109], v[134:135], v[106:107]
	v_pk_mul_f32 v[106:107], v[178:179], v[156:157] op_sel_hi:[1,0]
	v_pk_mul_f32 v[104:105], v[146:147], v[156:157] op_sel_hi:[1,0]
	v_pk_mul_f32 v[106:107], v[124:125], v[106:107]
	v_pk_mul_f32 v[104:105], v[126:127], v[104:105]
	v_cvt_pk_bf16_f32 v146, v110, v111
	v_cvt_pk_bf16_f32 v147, v108, v109
	v_cvt_pk_bf16_f32 v148, v106, v107
	v_cvt_pk_bf16_f32 v149, v104, v105
	v_pk_mul_f32 v[178:179], v[88:89], v[150:151] op_sel_hi:[1,0]
	global_store_dwordx4 v[182:183], v[146:149], off
	v_pk_mul_f32 v[84:85], v[84:85], v[150:151] op_sel_hi:[1,0]
	v_pk_mul_f32 v[186:187], v[80:81], v[150:151] op_sel_hi:[1,0]
	v_pk_mul_f32 v[148:149], v[90:91], v[150:151] op_sel_hi:[1,0]
	v_mov_b32_e32 v90, v93
	v_mov_b32_e32 v91, v179
	v_pk_mul_f32 v[94:95], v[94:95], v[150:151] op_sel_hi:[1,0]
	v_mov_b32_e32 v88, v92
	v_mov_b32_e32 v89, v178
	v_pk_mul_f32 v[90:91], v[90:91], v[90:91]
	v_pk_mul_f32 v[184:185], v[82:83], v[150:151] op_sel_hi:[1,0]
	v_mov_b32_e32 v82, v187
	v_mov_b32_e32 v83, v85
	v_pk_mul_f32 v[146:147], v[100:101], v[156:157] op_sel_hi:[1,0]
	v_pk_mul_f32 v[100:101], v[180:181], v[156:157] op_sel_hi:[1,0]
	v_pk_fma_f32 v[88:89], v[88:89], v[88:89], v[90:91]
	v_mov_b32_e32 v90, v94
	v_mov_b32_e32 v91, v148
	v_pk_mul_f32 v[180:181], v[86:87], v[150:151] op_sel_hi:[1,0]
	v_mov_b32_e32 v80, v186
	v_mov_b32_e32 v81, v84
	v_pk_mul_f32 v[82:83], v[82:83], v[82:83]
	v_pk_fma_f32 v[88:89], v[90:91], v[90:91], v[88:89]
	v_mov_b32_e32 v90, v95
	v_mov_b32_e32 v91, v149
	v_pk_fma_f32 v[80:81], v[80:81], v[80:81], v[82:83]
	v_mov_b32_e32 v82, v184
	v_mov_b32_e32 v83, v180
	v_pk_fma_f32 v[88:89], v[90:91], v[90:91], v[88:89]
	v_pk_fma_f32 v[80:81], v[82:83], v[82:83], v[80:81]
	v_mov_b32_e32 v82, v185
	v_mov_b32_e32 v83, v181
	v_pk_fma_f32 v[80:81], v[82:83], v[82:83], v[80:81]
	v_add_f32_e32 v82, v88, v89
	v_add_f32_e32 v81, v81, v82
	v_add_f32_e32 v88, v80, v81
	ds_bpermute_b32 v89, v176, v88
	v_pk_mul_f32 v[82:83], v[192:193], v[156:157] op_sel_hi:[1,0]
	v_pk_mul_f32 v[80:81], v[190:191], v[156:157] op_sel_hi:[1,0]
	v_pk_mul_f32 v[100:101], v[130:131], v[100:101]
	v_pk_mul_f32 v[86:87], v[128:129], v[146:147]
	s_waitcnt lgkmcnt(0)
; DI u32x2 pk4(f32x4 v) { u32x2 r; r.x = pk2(v[0], v[1]); r.y = pk2(v[2], v[3]); return r; }
; template <int REG>
; DI void epi_inproj(const Params& p, f32x4 (&acc)[2][2][4][2], int pm, int pn, LAS unsigned char* shm) {
;     ...
;       for (int m = 0; m < 4; ++m) { asm volatile("" ::: "memory");
;         const int r = 128 * ai + 64 * wr + 16 * m + fr, t = t0 + r;
;         const float rs = rsr[ai][m];
;         f32x4 v[2][2]; float ss = 0.f;
; #pragma unroll
;         for (int bj = 0; bj < 2; ++bj)
; #pragma unroll
;           for (int n = 0; n < 2; ++n) { v[bj][n] = acc[ai][bj][m][n] * rs; ss += v[bj][n][0] * v[bj][n][0] + v[bj][n][1] * v[bj][n][1] + v[bj][n][2] * v[bj][n][2] + v[bj][n][3] * v[bj][n][3]; }
;         ss += __shfl_xor(ss, 16); ss += __shfl_xor(ss, 32);
;         const float rn = __builtin_amdgcn_rsqf(ss * (1.0f / 64.0f) + 1e-6f) * (isk ? 1.0f : 0.125f * 1.4426950408889634f);
;         bf16_t* dst = dstb + ((long)((b * 8 + hh) * SEQ + t)) * 64 + 8 * fq;
; #pragma unroll
;         for (int bj = 0; bj < 2; ++bj) {
;           const f32x4 o0 = v[bj][0] * rn * w4[bj][0], o1 = v[bj][1] * rn * w4[bj][1]; cs4[bj][0] += o0; cs4[bj][1] += o1;
;           const u32x2 h0 = pk4(o0), h1 = pk4(o1);
;           *(u32x4*)(dst + 32 * bj) = (u32x4){h0.x, h0.y, h1.x, h1.y};
;         }
;       }
	v_add_f32_e32 v91, v88, v89
	ds_bpermute_b32 v145, v175, v91
	v_pk_mul_f32 v[80:81], v[118:119], v[80:81]
	v_pk_mul_f32 v[82:83], v[116:117], v[82:83]
	v_cvt_pk_bf16_f32 v88, v86, v87
	v_cvt_pk_bf16_f32 v89, v100, v101
	s_waitcnt lgkmcnt(0)
	v_add_f32_e32 v91, v91, v145
	v_fmamk_f32 v91, v91, 0x3c800000, v166
	v_rsq_f32_e32 v145, v91
	v_cvt_pk_bf16_f32 v90, v82, v83
	v_cvt_pk_bf16_f32 v91, v80, v81
	v_lshl_add_u64 v[182:183], v[182:183], 0, s[100:101]
	global_store_dwordx4 v[182:183], v[88:91], off offset:64
	v_mul_f32_e32 v150, v174, v145
	v_pk_mul_f32 v[60:61], v[60:61], v[112:113] op_sel_hi:[1,0]
	v_or_b32_e32 v88, 32, v144
	v_ashrrev_i32_e32 v89, 31, v88
	v_lshlrev_b64 v[88:89], 7, v[88:89]
	v_lshl_add_u64 v[182:183], v[142:143], 0, v[88:89]
	v_lshl_add_u64 v[182:183], v[182:183], 0, v[238:239]
	v_pk_mul_f32 v[88:89], v[92:93], v[150:151] op_sel_hi:[1,0]
	v_pk_mul_f32 v[90:91], v[94:95], v[150:151] op_sel_hi:[1,0]
	v_pk_mul_f32 v[94:95], v[132:133], v[88:89]
	v_pk_mul_f32 v[92:93], v[134:135], v[90:91]
	v_pk_mul_f32 v[90:91], v[178:179], v[150:151] op_sel_hi:[1,0]
	v_pk_mul_f32 v[88:89], v[148:149], v[150:151] op_sel_hi:[1,0]
	v_pk_mul_f32 v[90:91], v[124:125], v[90:91]
	v_pk_mul_f32 v[88:89], v[126:127], v[88:89]
	v_cvt_pk_bf16_f32 v146, v94, v95
	v_cvt_pk_bf16_f32 v147, v92, v93
	v_cvt_pk_bf16_f32 v148, v90, v91
	v_cvt_pk_bf16_f32 v149, v88, v89
	global_store_dwordx4 v[182:183], v[146:149], off
	v_pk_mul_f32 v[56:57], v[56:57], v[112:113] op_sel_hi:[1,0]
	v_pk_mul_f32 v[62:63], v[62:63], v[112:113] op_sel_hi:[1,0]
	v_mov_b32_e32 v148, v151
	v_pk_mul_f32 v[146:147], v[84:85], v[150:151] op_sel_hi:[1,0]
	v_pk_mul_f32 v[84:85], v[180:181], v[150:151] op_sel_hi:[1,0]
	v_pk_mul_f32 v[76:77], v[76:77], v[148:149] op_sel_hi:[1,0]
	v_pk_mul_f32 v[180:181], v[72:73], v[148:149] op_sel_hi:[1,0]
	v_pk_mul_f32 v[178:179], v[74:75], v[148:149] op_sel_hi:[1,0]
	v_mov_b32_e32 v74, v77
	v_mov_b32_e32 v75, v181
	v_pk_mul_f32 v[68:69], v[68:69], v[148:149] op_sel_hi:[1,0]
	v_pk_mul_f32 v[192:193], v[64:65], v[148:149] op_sel_hi:[1,0]
	v_pk_mul_f32 v[78:79], v[78:79], v[148:149] op_sel_hi:[1,0]
	v_mov_b32_e32 v72, v76
	v_mov_b32_e32 v73, v180
	v_pk_mul_f32 v[74:75], v[74:75], v[74:75]
	v_pk_mul_f32 v[190:191], v[66:67], v[148:149] op_sel_hi:[1,0]
	v_mov_b32_e32 v66, v193
	v_mov_b32_e32 v67, v69
	v_pk_fma_f32 v[72:73], v[72:73], v[72:73], v[74:75]
	v_mov_b32_e32 v74, v78
	v_mov_b32_e32 v75, v178
	v_pk_mul_f32 v[188:189], v[70:71], v[148:149] op_sel_hi:[1,0]
	v_mov_b32_e32 v64, v192
	v_mov_b32_e32 v65, v68
	v_pk_mul_f32 v[66:67], v[66:67], v[66:67]
	v_pk_fma_f32 v[72:73], v[74:75], v[74:75], v[72:73]
	v_mov_b32_e32 v74, v79
	v_mov_b32_e32 v75, v179
	v_pk_fma_f32 v[64:65], v[64:65], v[64:65], v[66:67]
	v_mov_b32_e32 v66, v190
	v_mov_b32_e32 v67, v188
	v_pk_fma_f32 v[72:73], v[74:75], v[74:75], v[72:73]
	v_pk_fma_f32 v[64:65], v[66:67], v[66:67], v[64:65]
	v_mov_b32_e32 v66, v191
	v_mov_b32_e32 v67, v189
	v_pk_fma_f32 v[64:65], v[66:67], v[66:67], v[64:65]
	v_add_f32_e32 v66, v72, v73
	v_add_f32_e32 v65, v65, v66
	v_add_f32_e32 v72, v64, v65
	ds_bpermute_b32 v73, v176, v72
	v_pk_mul_f32 v[66:67], v[186:187], v[150:151] op_sel_hi:[1,0]
	v_pk_mul_f32 v[64:65], v[184:185], v[150:151] op_sel_hi:[1,0]
	v_pk_mul_f32 v[84:85], v[130:131], v[84:85]
	v_pk_mul_f32 v[70:71], v[128:129], v[146:147]
	s_waitcnt lgkmcnt(0)
	v_add_f32_e32 v75, v72, v73
	ds_bpermute_b32 v145, v175, v75
	v_pk_mul_f32 v[64:65], v[118:119], v[64:65]
	v_pk_mul_f32 v[66:67], v[116:117], v[66:67]
	v_cvt_pk_bf16_f32 v72, v70, v71
	v_cvt_pk_bf16_f32 v73, v84, v85
	s_waitcnt lgkmcnt(0)
	v_add_f32_e32 v75, v75, v145
	v_fmamk_f32 v75, v75, 0x3c800000, v166
	v_rsq_f32_e32 v145, v75
	v_cvt_pk_bf16_f32 v74, v66, v67
	v_cvt_pk_bf16_f32 v75, v64, v65
	v_lshl_add_u64 v[182:183], v[182:183], 0, s[100:101]
	global_store_dwordx4 v[182:183], v[72:75], off offset:64
	v_mul_f32_e32 v156, v174, v145
	v_pk_mul_f32 v[186:187], v[48:49], v[112:113] op_sel_hi:[1,0]
	v_or_b32_e32 v72, 48, v144
	v_ashrrev_i32_e32 v73, 31, v72
	v_lshlrev_b64 v[72:73], 7, v[72:73]
	v_lshl_add_u64 v[182:183], v[142:143], 0, v[72:73]
	v_lshl_add_u64 v[182:183], v[182:183], 0, v[240:241]
	v_pk_mul_f32 v[72:73], v[76:77], v[156:157] op_sel_hi:[1,0]
	v_pk_mul_f32 v[74:75], v[78:79], v[156:157] op_sel_hi:[1,0]
	v_pk_mul_f32 v[146:147], v[132:133], v[72:73]
	v_pk_mul_f32 v[78:79], v[134:135], v[74:75]
	v_pk_mul_f32 v[72:73], v[180:181], v[156:157] op_sel_hi:[1,0]
	v_pk_mul_f32 v[74:75], v[178:179], v[156:157] op_sel_hi:[1,0]
	v_pk_mul_f32 v[76:77], v[124:125], v[72:73]
	v_pk_mul_f32 v[74:75], v[126:127], v[74:75]
	v_cvt_pk_bf16_f32 v148, v146, v147
	v_cvt_pk_bf16_f32 v149, v78, v79
	v_cvt_pk_bf16_f32 v150, v76, v77
	v_cvt_pk_bf16_f32 v151, v74, v75
	global_store_dwordx4 v[182:183], v[148:151], off
	v_pk_mul_f32 v[180:181], v[52:53], v[112:113] op_sel_hi:[1,0]
	v_pk_mul_f32 v[184:185], v[50:51], v[112:113] op_sel_hi:[1,0]
	v_mov_b32_e32 v150, v61
	v_mov_b32_e32 v151, v57
	v_pk_mul_f32 v[148:149], v[58:59], v[112:113] op_sel_hi:[1,0]
	v_mov_b32_e32 v58, v60
	v_mov_b32_e32 v59, v56
	v_pk_mul_f32 v[150:151], v[150:151], v[150:151]
	v_mov_b32_e32 v50, v187
	v_mov_b32_e32 v51, v181
	v_pk_fma_f32 v[58:59], v[58:59], v[58:59], v[150:151]
	v_mov_b32_e32 v150, v62
	v_mov_b32_e32 v151, v148
	v_pk_mul_f32 v[178:179], v[54:55], v[112:113] op_sel_hi:[1,0]
	v_mov_b32_e32 v48, v186
	v_mov_b32_e32 v49, v180
	v_pk_mul_f32 v[50:51], v[50:51], v[50:51]
	v_pk_fma_f32 v[58:59], v[150:151], v[150:151], v[58:59]
	v_mov_b32_e32 v150, v63
	v_mov_b32_e32 v151, v149
	v_pk_fma_f32 v[48:49], v[48:49], v[48:49], v[50:51]
	v_mov_b32_e32 v50, v184
	v_mov_b32_e32 v51, v178
	v_pk_fma_f32 v[58:59], v[150:151], v[150:151], v[58:59]
	v_pk_fma_f32 v[48:49], v[50:51], v[50:51], v[48:49]
	v_mov_b32_e32 v50, v185
	v_mov_b32_e32 v51, v179
	v_pk_fma_f32 v[48:49], v[50:51], v[50:51], v[48:49]
	v_add_f32_e32 v50, v58, v59
	v_add_f32_e32 v49, v49, v50
	v_add_f32_e32 v52, v48, v49
	ds_bpermute_b32 v53, v176, v52
	v_pk_mul_f32 v[72:73], v[68:69], v[156:157] op_sel_hi:[1,0]
	v_pk_mul_f32 v[68:69], v[188:189], v[156:157] op_sel_hi:[1,0]
	v_pk_mul_f32 v[50:51], v[192:193], v[156:157] op_sel_hi:[1,0]
	v_pk_mul_f32 v[48:49], v[190:191], v[156:157] op_sel_hi:[1,0]
	s_waitcnt lgkmcnt(0)
; DI u32x2 pk4(f32x4 v) { u32x2 r; r.x = pk2(v[0], v[1]); r.y = pk2(v[2], v[3]); return r; }
; template <int REG>
; DI void epi_inproj(const Params& p, f32x4 (&acc)[2][2][4][2], int pm, int pn, LAS unsigned char* shm) {
;     ...
;       for (int m = 0; m < 4; ++m) { asm volatile("" ::: "memory");
;         const int r = 128 * ai + 64 * wr + 16 * m + fr, t = t0 + r;
;         const float rs = rsr[ai][m];
;         f32x4 v[2][2]; float ss = 0.f;
; #pragma unroll
;         for (int bj = 0; bj < 2; ++bj)
; #pragma unroll
;           for (int n = 0; n < 2; ++n) { v[bj][n] = acc[ai][bj][m][n] * rs; ss += v[bj][n][0] * v[bj][n][0] + v[bj][n][1] * v[bj][n][1] + v[bj][n][2] * v[bj][n][2] + v[bj][n][3] * v[bj][n][3]; }
;         ss += __shfl_xor(ss, 16); ss += __shfl_xor(ss, 32);
;         const float rn = __builtin_amdgcn_rsqf(ss * (1.0f / 64.0f) + 1e-6f) * (isk ? 1.0f : 0.125f * 1.4426950408889634f);
;         bf16_t* dst = dstb + ((long)((b * 8 + hh) * SEQ + t)) * 64 + 8 * fq;
; #pragma unroll
;         for (int bj = 0; bj < 2; ++bj) {
;           const f32x4 o0 = v[bj][0] * rn * w4[bj][0], o1 = v[bj][1] * rn * w4[bj][1]; cs4[bj][0] += o0; cs4[bj][1] += o1;
;           const u32x2 h0 = pk4(o0), h1 = pk4(o1);
;           *(u32x4*)(dst + 32 * bj) = (u32x4){h0.x, h0.y, h1.x, h1.y};
;         }
;       }
	v_add_f32_e32 v58, v52, v53
	ds_bpermute_b32 v59, v175, v58
	v_pk_mul_f32 v[68:69], v[130:131], v[68:69]
	v_pk_mul_f32 v[72:73], v[128:129], v[72:73]
	v_pk_mul_f32 v[48:49], v[118:119], v[48:49]
	v_pk_mul_f32 v[50:51], v[116:117], v[50:51]
	s_waitcnt lgkmcnt(0)
	v_add_f32_e32 v58, v58, v59
	v_fmamk_f32 v58, v58, 0x3c800000, v166
	v_rsq_f32_e32 v58, v58
	v_cvt_pk_bf16_f32 v52, v72, v73
	v_cvt_pk_bf16_f32 v53, v68, v69
	v_cvt_pk_bf16_f32 v54, v50, v51
	v_cvt_pk_bf16_f32 v55, v48, v49
	v_lshl_add_u64 v[182:183], v[182:183], 0, s[100:101]
	global_store_dwordx4 v[182:183], v[52:55], off offset:64
	v_mul_f32_e32 v156, v174, v58
	v_pk_mul_f32 v[44:45], v[44:45], v[112:113] op_sel:[0,1]
	v_add_u32_e32 v52, 0x80, v144
	v_ashrrev_i32_e32 v53, 31, v52
	v_lshlrev_b64 v[52:53], 7, v[52:53]
	v_lshl_add_u64 v[182:183], v[142:143], 0, v[52:53]
	v_lshl_add_u64 v[182:183], v[182:183], 0, v[238:239]
	v_pk_mul_f32 v[52:53], v[60:61], v[156:157] op_sel_hi:[1,0]
	v_pk_mul_f32 v[54:55], v[62:63], v[156:157] op_sel_hi:[1,0]
	v_pk_mul_f32 v[60:61], v[132:133], v[52:53]
	v_pk_mul_f32 v[58:59], v[134:135], v[54:55]
	v_pk_mul_f32 v[52:53], v[56:57], v[156:157] op_sel_hi:[1,0]
	v_pk_mul_f32 v[54:55], v[148:149], v[156:157] op_sel_hi:[1,0]
	v_pk_mul_f32 v[56:57], v[124:125], v[52:53]
	v_pk_mul_f32 v[54:55], v[126:127], v[54:55]
	v_cvt_pk_bf16_f32 v148, v60, v61
	v_cvt_pk_bf16_f32 v149, v58, v59
	v_cvt_pk_bf16_f32 v150, v56, v57
	v_cvt_pk_bf16_f32 v151, v54, v55
	global_store_dwordx4 v[182:183], v[148:151], off
	v_pk_mul_f32 v[62:63], v[180:181], v[156:157] op_sel_hi:[1,0]
	v_pk_mul_f32 v[52:53], v[178:179], v[156:157] op_sel_hi:[1,0]
	v_pk_mul_f32 v[150:151], v[40:41], v[112:113] op_sel:[0,1]
	v_pk_mul_f32 v[46:47], v[46:47], v[112:113] op_sel:[0,1]
	v_pk_mul_f32 v[148:149], v[42:43], v[112:113] op_sel:[0,1]
	v_mov_b32_e32 v42, v45
	v_mov_b32_e32 v43, v151
	v_pk_mul_f32 v[178:179], v[38:39], v[112:113] op_sel:[0,1]
	v_pk_mul_f32 v[36:37], v[36:37], v[112:113] op_sel:[0,1]
	v_pk_mul_f32 v[180:181], v[34:35], v[112:113] op_sel:[0,1]
	v_pk_mul_f32 v[112:113], v[32:33], v[112:113] op_sel:[0,1]
	v_mov_b32_e32 v40, v44
	v_mov_b32_e32 v41, v150
	v_pk_mul_f32 v[42:43], v[42:43], v[42:43]
	v_mov_b32_e32 v34, v113
	v_mov_b32_e32 v35, v37
	v_pk_fma_f32 v[40:41], v[40:41], v[40:41], v[42:43]
	v_mov_b32_e32 v42, v46
	v_mov_b32_e32 v43, v148
	v_mov_b32_e32 v32, v112
	v_mov_b32_e32 v33, v36
	v_pk_mul_f32 v[34:35], v[34:35], v[34:35]
	v_pk_fma_f32 v[40:41], v[42:43], v[42:43], v[40:41]
	v_mov_b32_e32 v42, v47
	v_mov_b32_e32 v43, v149
	v_pk_fma_f32 v[32:33], v[32:33], v[32:33], v[34:35]
	v_mov_b32_e32 v34, v180
	v_mov_b32_e32 v35, v178
	v_pk_fma_f32 v[40:41], v[42:43], v[42:43], v[40:41]
	v_pk_fma_f32 v[32:33], v[34:35], v[34:35], v[32:33]
	v_mov_b32_e32 v34, v181
	v_mov_b32_e32 v35, v179
	v_pk_fma_f32 v[32:33], v[34:35], v[34:35], v[32:33]
	v_add_f32_e32 v34, v40, v41
	v_add_f32_e32 v33, v33, v34
	v_add_f32_e32 v40, v32, v33
	ds_bpermute_b32 v41, v176, v40
	v_pk_mul_f32 v[38:39], v[128:129], v[62:63]
	v_pk_mul_f32 v[34:35], v[186:187], v[156:157] op_sel_hi:[1,0]
	v_pk_mul_f32 v[32:33], v[184:185], v[156:157] op_sel_hi:[1,0]
	v_pk_mul_f32 v[52:53], v[130:131], v[52:53]
	s_waitcnt lgkmcnt(0)
	v_add_f32_e32 v43, v40, v41
	ds_bpermute_b32 v62, v175, v43
	v_pk_mul_f32 v[32:33], v[118:119], v[32:33]
	v_pk_mul_f32 v[34:35], v[116:117], v[34:35]
	v_cvt_pk_bf16_f32 v40, v38, v39
	v_cvt_pk_bf16_f32 v41, v52, v53
	s_waitcnt lgkmcnt(0)
	v_add_f32_e32 v43, v43, v62
	v_fmamk_f32 v43, v43, 0x3c800000, v166
	v_rsq_f32_e32 v62, v43
	v_cvt_pk_bf16_f32 v42, v34, v35
	v_cvt_pk_bf16_f32 v43, v32, v33
	v_lshl_add_u64 v[182:183], v[182:183], 0, s[100:101]
	global_store_dwordx4 v[182:183], v[40:43], off offset:64
	v_mul_f32_e32 v62, v174, v62
	v_pk_mul_f32 v[28:29], v[28:29], v[114:115] op_sel_hi:[1,0]
	v_add_u32_e32 v40, 0x90, v144
	v_ashrrev_i32_e32 v41, 31, v40
	v_lshlrev_b64 v[40:41], 7, v[40:41]
	v_lshl_add_u64 v[182:183], v[142:143], 0, v[40:41]
	v_lshl_add_u64 v[182:183], v[182:183], 0, v[240:241]
	v_pk_mul_f32 v[40:41], v[44:45], v[62:63] op_sel_hi:[1,0]
	v_pk_mul_f32 v[42:43], v[46:47], v[62:63] op_sel_hi:[1,0]
	v_pk_mul_f32 v[46:47], v[132:133], v[40:41]
	v_pk_mul_f32 v[44:45], v[134:135], v[42:43]
	v_pk_mul_f32 v[42:43], v[150:151], v[62:63] op_sel_hi:[1,0]
	v_pk_mul_f32 v[40:41], v[148:149], v[62:63] op_sel_hi:[1,0]
	v_pk_mul_f32 v[42:43], v[124:125], v[42:43]
	v_pk_mul_f32 v[40:41], v[126:127], v[40:41]
	v_cvt_pk_bf16_f32 v148, v46, v47
	v_cvt_pk_bf16_f32 v149, v44, v45
	v_cvt_pk_bf16_f32 v150, v42, v43
	v_cvt_pk_bf16_f32 v151, v40, v41
	global_store_dwordx4 v[182:183], v[148:151], off
	v_pk_mul_f32 v[20:21], v[20:21], v[114:115] op_sel_hi:[1,0]
	v_pk_mul_f32 v[188:189], v[16:17], v[114:115] op_sel_hi:[1,0]
	v_pk_mul_f32 v[148:149], v[36:37], v[62:63] op_sel_hi:[1,0]
	v_pk_mul_f32 v[36:37], v[178:179], v[62:63] op_sel_hi:[1,0]
	v_pk_mul_f32 v[178:179], v[24:25], v[114:115] op_sel_hi:[1,0]
	v_pk_mul_f32 v[150:151], v[26:27], v[114:115] op_sel_hi:[1,0]
	v_mov_b32_e32 v26, v29
	v_mov_b32_e32 v27, v179
	v_pk_mul_f32 v[30:31], v[30:31], v[114:115] op_sel_hi:[1,0]
	v_mov_b32_e32 v24, v28
	v_mov_b32_e32 v25, v178
	v_pk_mul_f32 v[26:27], v[26:27], v[26:27]
	v_pk_mul_f32 v[186:187], v[18:19], v[114:115] op_sel_hi:[1,0]
	v_mov_b32_e32 v18, v189
	v_mov_b32_e32 v19, v21
	v_pk_fma_f32 v[24:25], v[24:25], v[24:25], v[26:27]
	v_mov_b32_e32 v26, v30
	v_mov_b32_e32 v27, v150
	v_pk_mul_f32 v[184:185], v[22:23], v[114:115] op_sel_hi:[1,0]
	v_mov_b32_e32 v16, v188
	v_mov_b32_e32 v17, v20
	v_pk_mul_f32 v[18:19], v[18:19], v[18:19]
	v_pk_fma_f32 v[24:25], v[26:27], v[26:27], v[24:25]
	v_mov_b32_e32 v26, v31
	v_mov_b32_e32 v27, v151
	v_pk_fma_f32 v[16:17], v[16:17], v[16:17], v[18:19]
	v_mov_b32_e32 v18, v186
	v_mov_b32_e32 v19, v184
	v_pk_fma_f32 v[24:25], v[26:27], v[26:27], v[24:25]
	v_pk_fma_f32 v[16:17], v[18:19], v[18:19], v[16:17]
	v_mov_b32_e32 v18, v187
	v_mov_b32_e32 v19, v185
	v_pk_fma_f32 v[16:17], v[18:19], v[18:19], v[16:17]
	v_add_f32_e32 v18, v24, v25
	v_add_f32_e32 v17, v17, v18
	v_add_f32_e32 v24, v16, v17
	ds_bpermute_b32 v25, v176, v24
	v_pk_mul_f32 v[18:19], v[112:113], v[62:63] op_sel_hi:[1,0]
	v_pk_mul_f32 v[16:17], v[180:181], v[62:63] op_sel_hi:[1,0]
	v_pk_mul_f32 v[36:37], v[130:131], v[36:37]
	v_pk_mul_f32 v[22:23], v[128:129], v[148:149]
	s_waitcnt lgkmcnt(0)
; DI u32x2 pk4(f32x4 v) { u32x2 r; r.x = pk2(v[0], v[1]); r.y = pk2(v[2], v[3]); return r; }
; template <int REG>
; DI void epi_inproj(const Params& p, f32x4 (&acc)[2][2][4][2], int pm, int pn, LAS unsigned char* shm) {
;     ...
;       for (int m = 0; m < 4; ++m) { asm volatile("" ::: "memory");
;         const int r = 128 * ai + 64 * wr + 16 * m + fr, t = t0 + r;
;         const float rs = rsr[ai][m];
;         f32x4 v[2][2]; float ss = 0.f;
; #pragma unroll
;         for (int bj = 0; bj < 2; ++bj)
; #pragma unroll
;           for (int n = 0; n < 2; ++n) { v[bj][n] = acc[ai][bj][m][n] * rs; ss += v[bj][n][0] * v[bj][n][0] + v[bj][n][1] * v[bj][n][1] + v[bj][n][2] * v[bj][n][2] + v[bj][n][3] * v[bj][n][3]; }
;         ss += __shfl_xor(ss, 16); ss += __shfl_xor(ss, 32);
;         const float rn = __builtin_amdgcn_rsqf(ss * (1.0f / 64.0f) + 1e-6f) * (isk ? 1.0f : 0.125f * 1.4426950408889634f);
;         bf16_t* dst = dstb + ((long)((b * 8 + hh) * SEQ + t)) * 64 + 8 * fq;
; #pragma unroll
;         for (int bj = 0; bj < 2; ++bj) {
;           const f32x4 o0 = v[bj][0] * rn * w4[bj][0], o1 = v[bj][1] * rn * w4[bj][1]; cs4[bj][0] += o0; cs4[bj][1] += o1;
;           const u32x2 h0 = pk4(o0), h1 = pk4(o1);
;           *(u32x4*)(dst + 32 * bj) = (u32x4){h0.x, h0.y, h1.x, h1.y};
;         }
;       }
	v_add_f32_e32 v27, v24, v25
	ds_bpermute_b32 v62, v175, v27
	v_pk_mul_f32 v[16:17], v[118:119], v[16:17]
	v_pk_mul_f32 v[18:19], v[116:117], v[18:19]
	v_cvt_pk_bf16_f32 v24, v22, v23
	v_cvt_pk_bf16_f32 v25, v36, v37
	s_waitcnt lgkmcnt(0)
	v_add_f32_e32 v27, v27, v62
	v_fmamk_f32 v27, v27, 0x3c800000, v166
	v_rsq_f32_e32 v62, v27
	v_cvt_pk_bf16_f32 v26, v18, v19
	v_cvt_pk_bf16_f32 v27, v16, v17
	v_lshl_add_u64 v[182:183], v[182:183], 0, s[100:101]
	global_store_dwordx4 v[182:183], v[24:27], off offset:64
	v_mul_f32_e32 v112, v174, v62
	v_mov_b32_e32 v114, v115
	v_add_u32_e32 v24, 0xa0, v144
	v_ashrrev_i32_e32 v25, 31, v24
	v_lshlrev_b64 v[24:25], 7, v[24:25]
	v_lshl_add_u64 v[180:181], v[142:143], 0, v[24:25]
	v_lshl_add_u64 v[180:181], v[180:181], 0, v[238:239]
	v_pk_mul_f32 v[24:25], v[28:29], v[112:113] op_sel_hi:[1,0]
	v_pk_mul_f32 v[26:27], v[30:31], v[112:113] op_sel_hi:[1,0]
	v_pk_mul_f32 v[62:63], v[132:133], v[24:25]
	v_pk_mul_f32 v[28:29], v[134:135], v[26:27]
	v_pk_mul_f32 v[26:27], v[178:179], v[112:113] op_sel_hi:[1,0]
	v_pk_mul_f32 v[24:25], v[150:151], v[112:113] op_sel_hi:[1,0]
	v_pk_mul_f32 v[26:27], v[124:125], v[26:27]
	v_pk_mul_f32 v[24:25], v[126:127], v[24:25]
	v_cvt_pk_bf16_f32 v148, v62, v63
	v_cvt_pk_bf16_f32 v149, v28, v29
	v_cvt_pk_bf16_f32 v150, v26, v27
	v_cvt_pk_bf16_f32 v151, v24, v25
	global_store_dwordx4 v[180:181], v[148:151], off
	v_pk_mul_f32 v[12:13], v[12:13], v[114:115] op_sel_hi:[1,0]
	v_pk_mul_f32 v[30:31], v[20:21], v[112:113] op_sel_hi:[1,0]
	v_pk_mul_f32 v[150:151], v[8:9], v[114:115] op_sel_hi:[1,0]
	v_pk_mul_f32 v[20:21], v[184:185], v[112:113] op_sel_hi:[1,0]
	v_pk_mul_f32 v[148:149], v[10:11], v[114:115] op_sel_hi:[1,0]
	v_mov_b32_e32 v10, v13
	v_mov_b32_e32 v11, v151
	v_pk_mul_f32 v[182:183], v[4:5], v[114:115] op_sel_hi:[1,0]
	v_pk_mul_f32 v[184:185], v[0:1], v[114:115] op_sel_hi:[1,0]
	v_pk_mul_f32 v[14:15], v[14:15], v[114:115] op_sel_hi:[1,0]
	v_mov_b32_e32 v8, v12
	v_mov_b32_e32 v9, v150
	v_pk_mul_f32 v[10:11], v[10:11], v[10:11]
	v_mov_b32_e32 v4, v185
	v_mov_b32_e32 v5, v183
	v_pk_fma_f32 v[8:9], v[8:9], v[8:9], v[10:11]
	v_mov_b32_e32 v10, v14
	v_mov_b32_e32 v11, v148
	v_pk_mul_f32 v[178:179], v[6:7], v[114:115] op_sel_hi:[1,0]
	v_pk_mul_f32 v[2:3], v[2:3], v[114:115] op_sel_hi:[1,0]
	v_mov_b32_e32 v0, v184
	v_mov_b32_e32 v1, v182
	v_pk_mul_f32 v[4:5], v[4:5], v[4:5]
	v_pk_fma_f32 v[8:9], v[10:11], v[10:11], v[8:9]
	v_mov_b32_e32 v10, v15
	v_mov_b32_e32 v11, v149
	v_pk_fma_f32 v[0:1], v[0:1], v[0:1], v[4:5]
	v_mov_b32_e32 v4, v2
	v_mov_b32_e32 v5, v178
	v_pk_fma_f32 v[8:9], v[10:11], v[10:11], v[8:9]
	v_pk_fma_f32 v[0:1], v[4:5], v[4:5], v[0:1]
	v_mov_b32_e32 v4, v3
	v_mov_b32_e32 v5, v179
	v_pk_fma_f32 v[0:1], v[4:5], v[4:5], v[0:1]
	v_add_f32_e32 v4, v8, v9
	v_add_f32_e32 v1, v1, v4
	v_add_f32_e32 v6, v0, v1
	ds_bpermute_b32 v7, v176, v6
	v_pk_mul_f32 v[10:11], v[128:129], v[30:31]
	v_pk_mul_f32 v[4:5], v[188:189], v[112:113] op_sel_hi:[1,0]
	v_pk_mul_f32 v[0:1], v[186:187], v[112:113] op_sel_hi:[1,0]
	v_pk_mul_f32 v[20:21], v[130:131], v[20:21]
	s_waitcnt lgkmcnt(0)
	v_add_f32_e32 v9, v6, v7
	ds_bpermute_b32 v30, v175, v9
	v_pk_mul_f32 v[0:1], v[118:119], v[0:1]
	v_pk_mul_f32 v[4:5], v[116:117], v[4:5]
	v_cvt_pk_bf16_f32 v6, v10, v11
	v_cvt_pk_bf16_f32 v7, v20, v21
	s_waitcnt lgkmcnt(0)
	v_add_f32_e32 v9, v9, v30
	v_fmamk_f32 v9, v9, 0x3c800000, v166
	v_rsq_f32_e32 v30, v9
	v_cvt_pk_bf16_f32 v8, v4, v5
	v_cvt_pk_bf16_f32 v9, v0, v1
	v_lshl_add_u64 v[180:181], v[180:181], 0, s[100:101]
	global_store_dwordx4 v[180:181], v[6:9], off offset:64
	v_mul_f32_e32 v156, v174, v30
	v_pk_mul_f32 v[2:3], v[2:3], v[156:157] op_sel_hi:[1,0]
	v_add_u32_e32 v6, 0xb0, v144
	v_ashrrev_i32_e32 v7, 31, v6
	v_lshlrev_b64 v[6:7], 7, v[6:7]
	v_lshl_add_u64 v[142:143], v[142:143], 0, v[6:7]
	v_lshl_add_u64 v[142:143], v[142:143], 0, v[240:241]
	v_pk_mul_f32 v[6:7], v[12:13], v[156:157] op_sel_hi:[1,0]
	v_pk_mul_f32 v[8:9], v[14:15], v[156:157] op_sel_hi:[1,0]
	v_pk_mul_f32 v[114:115], v[132:133], v[6:7]
	v_pk_mul_f32 v[112:113], v[134:135], v[8:9]
	v_pk_mul_f32 v[6:7], v[150:151], v[156:157] op_sel_hi:[1,0]
	v_pk_mul_f32 v[8:9], v[148:149], v[156:157] op_sel_hi:[1,0]
	v_pk_mul_f32 v[30:31], v[124:125], v[6:7]
	v_pk_mul_f32 v[14:15], v[126:127], v[8:9]
	v_cvt_pk_bf16_f32 v6, v114, v115
	v_cvt_pk_bf16_f32 v7, v112, v113
	v_cvt_pk_bf16_f32 v8, v30, v31
	v_cvt_pk_bf16_f32 v9, v14, v15
	global_store_dwordx4 v[142:143], v[6:9], off
	v_pk_mul_f32 v[2:3], v[118:119], v[2:3]
	s_nop 0
	v_pk_mul_f32 v[6:7], v[182:183], v[156:157] op_sel_hi:[1,0]
	v_pk_mul_f32 v[8:9], v[178:179], v[156:157] op_sel_hi:[1,0]
	v_pk_mul_f32 v[12:13], v[128:129], v[6:7]
	v_pk_mul_f32 v[6:7], v[184:185], v[156:157] op_sel_hi:[1,0]
	v_pk_mul_f32 v[8:9], v[130:131], v[8:9]
	v_pk_mul_f32 v[6:7], v[116:117], v[6:7]
	v_cvt_pk_bf16_f32 v116, v12, v13
	v_cvt_pk_bf16_f32 v117, v8, v9
	v_cvt_pk_bf16_f32 v118, v6, v7
	v_cvt_pk_bf16_f32 v119, v2, v3
	v_lshl_add_u64 v[142:143], v[142:143], 0, s[100:101]
	global_store_dwordx4 v[142:143], v[116:119], off offset:64
	s_cbranch_scc1 .LBB0_471
; template <int REG>
; DI void epi_inproj(const Params& p, f32x4 (&acc)[2][2][4][2], int pm, int pn, LAS unsigned char* shm) {
;     ...
;           const f32x4 o0 = v[bj][0] * rn * w4[bj][0], o1 = v[bj][1] * rn * w4[bj][1]; cs4[bj][0] += o0; cs4[bj][1] += o1;
;     ...
;       for (int bj = 0; bj < 2; ++bj)
; #pragma unroll
;         for (int n = 0; n < 2; ++n)
; #pragma unroll
;           for (int j = 0; j < 4; ++j) {
;             float s = cs4[bj][n][j];
;             s += __shfl_xor(s, 1); s += __shfl_xor(s, 2); s += __shfl_xor(s, 4); s += __shfl_xor(s, 8);
;             if (fr == 0) red[wr * 256 + wc * 64 + 32 * bj + 8 * fq + 4 * n + j] = s;
;           }
	s_nop 1
	v_pk_add_f32 v[116:117], v[140:141], 0 op_sel_hi:[1,0]
	s_nop 0
	v_pk_add_f32 v[110:111], v[116:117], v[110:111]
	s_nop 0
	v_pk_add_f32 v[94:95], v[110:111], v[94:95]
	s_nop 0
	v_pk_add_f32 v[94:95], v[94:95], v[146:147]
	s_nop 0
	v_pk_add_f32 v[60:61], v[94:95], v[60:61]
	s_nop 0
	v_pk_add_f32 v[46:47], v[60:61], v[46:47]
	s_nop 0
	v_pk_add_f32 v[46:47], v[46:47], v[62:63]
	s_nop 0
	v_pk_add_f32 v[46:47], v[46:47], v[114:115]
	s_nop 0
	v_lshlrev_b32_e32 v110, 8, v173
	v_and_b32_e32 v63, 0x3fffff00, v168
	v_lshlrev_b32_e32 v63, 2, v63
	v_add3_u32 v63, s77, v63, v110
	v_add_u32_e32 v63, v63, v171
	v_cmp_eq_u32_e32 vcc, 0, v170
	v_add_f32_dpp v46, v46, v46 quad_perm:[1,0,3,2] row_mask:0xf bank_mask:0xf
	v_add_f32_dpp v47, v47, v47 quad_perm:[1,0,3,2] row_mask:0xf bank_mask:0xf
	s_nop 0
	v_add_f32_dpp v46, v46, v46 quad_perm:[2,3,0,1] row_mask:0xf bank_mask:0xf
	v_add_f32_dpp v47, v47, v47 quad_perm:[2,3,0,1] row_mask:0xf bank_mask:0xf
	s_nop 0
	v_add_f32_dpp v46, v46, v46 row_half_mirror row_mask:0xf bank_mask:0xf
	v_add_f32_dpp v47, v47, v47 row_half_mirror row_mask:0xf bank_mask:0xf
	s_nop 0
	v_add_f32_dpp v46, v46, v46 row_mirror row_mask:0xf bank_mask:0xf
	v_add_f32_dpp v47, v47, v47 row_mirror row_mask:0xf bank_mask:0xf
	s_nop 0
	s_and_saveexec_b64 s[22:23], vcc
	ds_write_b64 v63, v[46:47]
	s_or_b64 exec, exec, s[22:23]
	v_pk_add_f32 v[94:95], v[138:139], 0 op_sel_hi:[1,0]
	s_nop 0
	v_pk_add_f32 v[94:95], v[94:95], v[108:109]
	s_nop 0
	v_pk_add_f32 v[92:93], v[94:95], v[92:93]
	s_nop 0
	v_pk_add_f32 v[92:93], v[92:93], v[78:79]
	s_nop 0
	v_pk_add_f32 v[58:59], v[92:93], v[58:59]
	s_nop 0
	v_pk_add_f32 v[44:45], v[58:59], v[44:45]
	s_nop 0
	v_pk_add_f32 v[28:29], v[44:45], v[28:29]
	s_nop 0
	v_pk_add_f32 v[28:29], v[28:29], v[112:113]
	s_nop 0
	s_nop 0
	v_add_f32_dpp v28, v28, v28 quad_perm:[1,0,3,2] row_mask:0xf bank_mask:0xf
	v_add_f32_dpp v29, v29, v29 quad_perm:[1,0,3,2] row_mask:0xf bank_mask:0xf
	s_nop 0
	v_add_f32_dpp v28, v28, v28 quad_perm:[2,3,0,1] row_mask:0xf bank_mask:0xf
	v_add_f32_dpp v29, v29, v29 quad_perm:[2,3,0,1] row_mask:0xf bank_mask:0xf
	s_nop 0
	v_add_f32_dpp v28, v28, v28 row_half_mirror row_mask:0xf bank_mask:0xf
	v_add_f32_dpp v29, v29, v29 row_half_mirror row_mask:0xf bank_mask:0xf
	s_nop 0
	v_add_f32_dpp v28, v28, v28 row_mirror row_mask:0xf bank_mask:0xf
	v_add_f32_dpp v29, v29, v29 row_mirror row_mask:0xf bank_mask:0xf
	s_nop 0
	s_and_saveexec_b64 s[22:23], vcc
	ds_write_b64 v63, v[28:29] offset:8
	s_or_b64 exec, exec, s[22:23]
	v_pk_add_f32 v[28:29], v[136:137], 0 op_sel_hi:[1,0]
	s_nop 0
	v_pk_add_f32 v[28:29], v[28:29], v[106:107]
	s_nop 0
	v_pk_add_f32 v[28:29], v[28:29], v[90:91]
	s_nop 0
	v_pk_add_f32 v[28:29], v[28:29], v[76:77]
	s_nop 0
	v_pk_add_f32 v[28:29], v[28:29], v[56:57]
	s_nop 0
	v_pk_add_f32 v[28:29], v[28:29], v[42:43]
	s_nop 0
	v_pk_add_f32 v[26:27], v[28:29], v[26:27]
	s_nop 0
	v_pk_add_f32 v[26:27], v[26:27], v[30:31]
	s_nop 0
	s_nop 0
	v_add_f32_dpp v26, v26, v26 quad_perm:[1,0,3,2] row_mask:0xf bank_mask:0xf
	v_add_f32_dpp v27, v27, v27 quad_perm:[1,0,3,2] row_mask:0xf bank_mask:0xf
	s_nop 0
	v_add_f32_dpp v26, v26, v26 quad_perm:[2,3,0,1] row_mask:0xf bank_mask:0xf
	v_add_f32_dpp v27, v27, v27 quad_perm:[2,3,0,1] row_mask:0xf bank_mask:0xf
	s_nop 0
	v_add_f32_dpp v26, v26, v26 row_half_mirror row_mask:0xf bank_mask:0xf
	v_add_f32_dpp v27, v27, v27 row_half_mirror row_mask:0xf bank_mask:0xf
	s_nop 0
	v_add_f32_dpp v26, v26, v26 row_mirror row_mask:0xf bank_mask:0xf
	v_add_f32_dpp v27, v27, v27 row_mirror row_mask:0xf bank_mask:0xf
	s_nop 0
	s_and_saveexec_b64 s[22:23], vcc
	ds_write_b64 v63, v[26:27] offset:16
	s_or_b64 exec, exec, s[22:23]
	v_pk_add_f32 v[26:27], v[122:123], 0 op_sel_hi:[1,0]
	s_nop 0
	v_pk_add_f32 v[26:27], v[26:27], v[104:105]
	s_nop 0
	v_pk_add_f32 v[26:27], v[26:27], v[88:89]
	s_nop 0
	v_pk_add_f32 v[28:29], v[26:27], v[74:75]
	s_nop 0
	v_pk_add_f32 v[28:29], v[28:29], v[54:55]
	s_nop 0
	v_pk_add_f32 v[28:29], v[28:29], v[40:41]
	s_nop 0
	v_pk_add_f32 v[24:25], v[28:29], v[24:25]
	s_nop 0
	v_pk_add_f32 v[14:15], v[24:25], v[14:15]
	s_nop 0
	s_nop 0
	v_add_f32_dpp v14, v14, v14 quad_perm:[1,0,3,2] row_mask:0xf bank_mask:0xf
	v_add_f32_dpp v15, v15, v15 quad_perm:[1,0,3,2] row_mask:0xf bank_mask:0xf
	s_nop 0
	v_add_f32_dpp v14, v14, v14 quad_perm:[2,3,0,1] row_mask:0xf bank_mask:0xf
	v_add_f32_dpp v15, v15, v15 quad_perm:[2,3,0,1] row_mask:0xf bank_mask:0xf
	s_nop 0
	v_add_f32_dpp v14, v14, v14 row_half_mirror row_mask:0xf bank_mask:0xf
	v_add_f32_dpp v15, v15, v15 row_half_mirror row_mask:0xf bank_mask:0xf
	s_nop 0
	v_add_f32_dpp v14, v14, v14 row_mirror row_mask:0xf bank_mask:0xf
	v_add_f32_dpp v15, v15, v15 row_mirror row_mask:0xf bank_mask:0xf
	s_nop 0
	s_and_saveexec_b64 s[22:23], vcc
	ds_write_b64 v63, v[14:15] offset:24
	s_or_b64 exec, exec, s[22:23]
	v_pk_add_f32 v[14:15], v[102:103], 0 op_sel_hi:[1,0]
	s_nop 0
	v_pk_add_f32 v[14:15], v[14:15], v[86:87]
	s_nop 0
; template <int REG>
; DI void epi_inproj(const Params& p, f32x4 (&acc)[2][2][4][2], int pm, int pn, LAS unsigned char* shm) {
;     ...
;       for (int bj = 0; bj < 2; ++bj)
; #pragma unroll
;         for (int n = 0; n < 2; ++n)
; #pragma unroll
;           for (int j = 0; j < 4; ++j) {
;             float s = cs4[bj][n][j];
;             s += __shfl_xor(s, 1); s += __shfl_xor(s, 2); s += __shfl_xor(s, 4); s += __shfl_xor(s, 8);
;             if (fr == 0) red[wr * 256 + wc * 64 + 32 * bj + 8 * fq + 4 * n + j] = s;
;           }
;       __syncthreads();
;       if (tid < 256) {
;         float* kbar = (float*)(ws + OFF_KBAR);
;         kbar[((long)((b * 8 + (pn & 1) * 4 + (tid >> 6)) * 32 + blk)) * 64 + (tid & 63)] = (red[tid] + red[256 + tid]) * (1.0f / 256.0f);
	v_pk_add_f32 v[14:15], v[14:15], v[70:71]
	s_nop 0
	v_pk_add_f32 v[14:15], v[14:15], v[72:73]
	s_nop 0
	v_pk_add_f32 v[14:15], v[14:15], v[38:39]
	s_nop 0
	v_pk_add_f32 v[14:15], v[14:15], v[22:23]
	s_nop 0
	v_pk_add_f32 v[10:11], v[14:15], v[10:11]
	s_nop 0
	v_pk_add_f32 v[10:11], v[10:11], v[12:13]
	s_nop 0
	s_nop 0
	v_add_f32_dpp v10, v10, v10 quad_perm:[1,0,3,2] row_mask:0xf bank_mask:0xf
	v_add_f32_dpp v11, v11, v11 quad_perm:[1,0,3,2] row_mask:0xf bank_mask:0xf
	s_nop 0
	v_add_f32_dpp v10, v10, v10 quad_perm:[2,3,0,1] row_mask:0xf bank_mask:0xf
	v_add_f32_dpp v11, v11, v11 quad_perm:[2,3,0,1] row_mask:0xf bank_mask:0xf
	s_nop 0
	v_add_f32_dpp v10, v10, v10 row_half_mirror row_mask:0xf bank_mask:0xf
	v_add_f32_dpp v11, v11, v11 row_half_mirror row_mask:0xf bank_mask:0xf
	s_nop 0
	v_add_f32_dpp v10, v10, v10 row_mirror row_mask:0xf bank_mask:0xf
	v_add_f32_dpp v11, v11, v11 row_mirror row_mask:0xf bank_mask:0xf
	s_nop 0
	s_and_saveexec_b64 s[22:23], vcc
	ds_write_b64 v63, v[10:11] offset:128
	s_or_b64 exec, exec, s[22:23]
	v_pk_add_f32 v[10:11], v[120:121], 0 op_sel_hi:[1,0]
	s_nop 0
	v_pk_add_f32 v[10:11], v[10:11], v[100:101]
	s_nop 0
	v_pk_add_f32 v[10:11], v[10:11], v[84:85]
	s_nop 0
	v_pk_add_f32 v[12:13], v[10:11], v[68:69]
	s_nop 0
	v_pk_add_f32 v[12:13], v[12:13], v[52:53]
	s_nop 0
	v_pk_add_f32 v[12:13], v[12:13], v[36:37]
	s_nop 0
	v_pk_add_f32 v[12:13], v[12:13], v[20:21]
	s_nop 0
	v_pk_add_f32 v[8:9], v[12:13], v[8:9]
	s_nop 0
	s_nop 0
	v_add_f32_dpp v8, v8, v8 quad_perm:[1,0,3,2] row_mask:0xf bank_mask:0xf
	v_add_f32_dpp v9, v9, v9 quad_perm:[1,0,3,2] row_mask:0xf bank_mask:0xf
	s_nop 0
	v_add_f32_dpp v8, v8, v8 quad_perm:[2,3,0,1] row_mask:0xf bank_mask:0xf
	v_add_f32_dpp v9, v9, v9 quad_perm:[2,3,0,1] row_mask:0xf bank_mask:0xf
	s_nop 0
	v_add_f32_dpp v8, v8, v8 row_half_mirror row_mask:0xf bank_mask:0xf
	v_add_f32_dpp v9, v9, v9 row_half_mirror row_mask:0xf bank_mask:0xf
	s_nop 0
	v_add_f32_dpp v8, v8, v8 row_mirror row_mask:0xf bank_mask:0xf
	v_add_f32_dpp v9, v9, v9 row_mirror row_mask:0xf bank_mask:0xf
	s_nop 0
	s_and_saveexec_b64 s[22:23], vcc
	ds_write_b64 v63, v[8:9] offset:136
	s_or_b64 exec, exec, s[22:23]
	v_pk_add_f32 v[8:9], v[98:99], 0 op_sel_hi:[1,0]
	s_nop 0
	v_pk_add_f32 v[8:9], v[8:9], v[82:83]
	s_nop 0
	v_pk_add_f32 v[8:9], v[8:9], v[66:67]
	s_nop 0
	v_pk_add_f32 v[8:9], v[8:9], v[50:51]
	s_nop 0
	v_pk_add_f32 v[8:9], v[8:9], v[34:35]
	s_nop 0
	v_pk_add_f32 v[8:9], v[8:9], v[18:19]
	s_nop 0
	v_pk_add_f32 v[4:5], v[8:9], v[4:5]
	s_nop 0
	v_pk_add_f32 v[4:5], v[4:5], v[6:7]
	s_nop 0
	s_nop 0
	v_add_f32_dpp v4, v4, v4 quad_perm:[1,0,3,2] row_mask:0xf bank_mask:0xf
	v_add_f32_dpp v5, v5, v5 quad_perm:[1,0,3,2] row_mask:0xf bank_mask:0xf
	s_nop 0
	v_add_f32_dpp v4, v4, v4 quad_perm:[2,3,0,1] row_mask:0xf bank_mask:0xf
	v_add_f32_dpp v5, v5, v5 quad_perm:[2,3,0,1] row_mask:0xf bank_mask:0xf
	s_nop 0
	v_add_f32_dpp v4, v4, v4 row_half_mirror row_mask:0xf bank_mask:0xf
	v_add_f32_dpp v5, v5, v5 row_half_mirror row_mask:0xf bank_mask:0xf
	s_nop 0
	v_add_f32_dpp v4, v4, v4 row_mirror row_mask:0xf bank_mask:0xf
	v_add_f32_dpp v5, v5, v5 row_mirror row_mask:0xf bank_mask:0xf
	s_nop 0
	s_and_saveexec_b64 s[22:23], vcc
	ds_write_b64 v63, v[4:5] offset:144
	s_or_b64 exec, exec, s[22:23]
	v_pk_add_f32 v[4:5], v[96:97], 0 op_sel_hi:[1,0]
	s_nop 0
	v_pk_add_f32 v[4:5], v[4:5], v[80:81]
	s_nop 0
	v_pk_add_f32 v[4:5], v[4:5], v[64:65]
	s_nop 0
	v_pk_add_f32 v[6:7], v[4:5], v[48:49]
	s_nop 0
	v_pk_add_f32 v[6:7], v[6:7], v[32:33]
	s_nop 0
	v_pk_add_f32 v[6:7], v[6:7], v[16:17]
	s_nop 0
	v_pk_add_f32 v[0:1], v[6:7], v[0:1]
	s_nop 0
	v_pk_add_f32 v[0:1], v[0:1], v[2:3]
	s_nop 0
	s_nop 0
	v_add_f32_dpp v0, v0, v0 quad_perm:[1,0,3,2] row_mask:0xf bank_mask:0xf
	v_add_f32_dpp v1, v1, v1 quad_perm:[1,0,3,2] row_mask:0xf bank_mask:0xf
	s_nop 0
	v_add_f32_dpp v0, v0, v0 quad_perm:[2,3,0,1] row_mask:0xf bank_mask:0xf
	v_add_f32_dpp v1, v1, v1 quad_perm:[2,3,0,1] row_mask:0xf bank_mask:0xf
	s_nop 0
	v_add_f32_dpp v0, v0, v0 row_half_mirror row_mask:0xf bank_mask:0xf
	v_add_f32_dpp v1, v1, v1 row_half_mirror row_mask:0xf bank_mask:0xf
	s_nop 0
	v_add_f32_dpp v0, v0, v0 row_mirror row_mask:0xf bank_mask:0xf
	v_add_f32_dpp v1, v1, v1 row_mirror row_mask:0xf bank_mask:0xf
	s_nop 0
	s_and_saveexec_b64 s[22:23], vcc
	ds_write_b64 v63, v[0:1] offset:152
	s_or_b64 exec, exec, s[22:23]
	v_cmp_gt_i32_e32 vcc, s64, v168
	s_waitcnt lgkmcnt(0)
	s_barrier
	s_and_saveexec_b64 s[22:23], vcc
	s_cbranch_execz .LBB0_470
	v_lshl_add_u32 v0, v168, 2, 0
	v_add_u32_e32 v0, 0x20000, v0
	ds_read2st64_b32 v[0:1], v0 offset1:4
	v_add_u32_e32 v2, s47, v169
	v_lshl_or_b32 v2, v2, 5, s46
	v_ashrrev_i32_e32 v3, 31, v2
	v_and_b32_e32 v4, 63, v168
	s_waitcnt lgkmcnt(0)
	v_add_f32_e32 v0, v0, v1
	v_mul_f32_e32 v5, 0x3b800000, v0
	v_lshlrev_b64 v[0:1], 8, v[2:3]
	v_lshl_add_u64 v[0:1], s[8:9], 0, v[0:1]
	v_lshlrev_b32_e32 v156, 2, v4
	v_lshl_add_u64 v[0:1], v[0:1], 0, v[156:157]
	global_store_dword v[0:1], v5, off
